# sample-row adaLN epilogue: the 12 dot products read the LDS-resident weight vectors and reduce by DPP (they re-read L2 per dot and reduced through ds_bpermute)
# speedup vs baseline: 1.0142x; 1.0061x over previous
;     DEVI float* mod() const { return (float*)(ws + WS_MOD); }
;     DEVI float* rstd() const { return (float*)(ws + WS_RSTD); }
;     DEVI bf16_t* hb() const { return (bf16_t*)(ws + WS_HB); }
; DEVI unsigned pk2bf(float lo, float hi) { unsigned r; asm volatile("v_cvt_pk_bf16_f32 %0, %1, %2" : "=v"(r) : "v"(lo), "v"(hi)); return r; }
; template <int WHICH> DEVI void adaln_apply(const P& p, int l, int r, int lane_in, float (&v)[16]) {
;     ...
;     const float rstd = rsqrtf(wave_sum(ss) * (1.f / D) + EPS);
;     const float* md = p.mod() + ((size_t)l * NSEQ + row_seq(r)) * 6144 + 16 * lane;
; #pragma unroll
;     for (int q = 0; q < 4; ++q) {
;         const float4 gg = *(const float4*)(g + 4 * q), sc = *(const float4*)(md + osc + 4 * q), sh = *(const float4*)(md + osh + 4 * q);
;         v[4 * q] = v[4 * q] * rstd * gg.x * (1.f + sc.x) + sh.x; v[4 * q + 1] = v[4 * q + 1] * rstd * gg.y * (1.f + sc.y) + sh.y;
;         v[4 * q + 2] = v[4 * q + 2] * rstd * gg.z * (1.f + sc.z) + sh.z; v[4 * q + 3] = v[4 * q + 3] * rstd * gg.w * (1.f + sc.w) + sh.w;
;     }
;     u32x4_t* ob = (u32x4_t*)(p.hb() + (size_t)r * D + 16 * lane);
;     ob[0] = (u32x4_t){pk2bf(v[0], v[1]), pk2bf(v[2], v[3]), pk2bf(v[4], v[5]), pk2bf(v[6], v[7])};
;     ob[1] = (u32x4_t){pk2bf(v[8], v[9]), pk2bf(v[10], v[11]), pk2bf(v[12], v[13]), pk2bf(v[14], v[15])};
;     ...
;         for (int jj = 0; jj < 12; ++jj) { float a = 0.f;
; #pragma unroll
;             for (int q = 0; q < 4; ++q) { const float4 w = *(const float4*)(ws + (size_t)jj * D + 4 * q); a += v[4 * q] * w.x + v[4 * q + 1] * w.y + v[4 * q + 2] * w.z + v[4 * q + 3] * w.w; }
.LBB0_1151:
	v_lshlrev_b32_e32 v58, 4, v54
	s_lshl_b64 s[30:31], s[8:9], 2
	v_ashrrev_i32_e32 v59, 31, v58
	s_add_u32 s28, s28, s30
	s_addc_u32 s29, s29, s31
	v_lshlrev_b64 v[56:57], 2, v[58:59]
	s_waitcnt lgkmcnt(0)
	v_add_f32_e32 v2, v2, v3
	v_lshl_add_u64 v[4:5], s[28:29], 0, v[56:57]
	v_fmamk_f32 v2, v2, 0x3a800000, v211
	s_mov_b32 s28, 0x800000
	v_cmp_gt_f32_e32 vcc, s28, v2
	s_ashr_i32 s28, s41, 31
	v_mul_f32_e32 v3, 0x4b800000, v2
	s_add_u32 s29, s47, s41
	v_cndmask_b32_e32 v2, v2, v3, vcc
	s_addc_u32 s28, s46, s28
	v_rsq_f32_e32 v2, v2
	s_mulk_i32 s28, 0x6000
	s_mul_hi_u32 s30, s29, 0x6000
	s_add_i32 s30, s30, s28
	s_mulk_i32 s29, 0x6000
	s_add_u32 s28, s48, s29
	s_addc_u32 s29, s49, s30
	v_mul_f32_e32 v3, 0x45800000, v2
	v_lshl_add_u64 v[14:15], s[28:29], 0, v[56:57]
	s_movk_i32 s28, 0x1000
	v_cndmask_b32_e32 v55, v2, v3, vcc
	s_mov_b64 s[40:41], 0x1000
	global_load_dwordx4 v[26:29], v[4:5], off offset:48
	global_load_dwordx4 v[42:45], v[4:5], off offset:32
	global_load_dwordx4 v[50:53], v[4:5], off offset:16
	global_load_dwordx4 v[60:63], v[4:5], off
	v_add_co_u32_e32 v4, vcc, s28, v14
	v_lshl_add_u64 v[2:3], v[14:15], 0, s[40:41]
	s_nop 0
	v_addc_co_u32_e32 v5, vcc, 0, v15, vcc
	global_load_dwordx4 v[68:71], v[4:5], off
	global_load_dwordx4 v[38:41], v[2:3], off offset:48
	global_load_dwordx4 v[46:49], v[2:3], off offset:32
	global_load_dwordx4 v[72:75], v[2:3], off offset:16
	s_nop 0
	global_load_dwordx4 v[2:5], v[14:15], off offset:48
	global_load_dwordx4 v[6:9], v[14:15], off offset:32
	global_load_dwordx4 v[10:13], v[14:15], off offset:16
	s_nop 0
	global_load_dwordx4 v[14:17], v[14:15], off
	v_mul_f32_e32 v34, v34, v55
	v_mul_f32_e32 v30, v30, v55
	s_lshl_b64 s[28:29], s[24:25], 11
	s_add_u32 s28, s50, s28
	s_addc_u32 s29, s51, s29
	s_waitcnt vmcnt(9)
	v_mul_f32_e32 v30, v30, v50
	s_waitcnt vmcnt(8)
	v_mul_f32_e32 v34, v34, v60
	s_waitcnt vmcnt(7)
	v_add_f32_e32 v60, 1.0, v68
	s_waitcnt vmcnt(0)
	v_fma_f32 v14, v34, v60, v14
	v_mul_f32_e32 v34, v35, v55
	v_mul_f32_e32 v34, v34, v61
	v_add_f32_e32 v35, 1.0, v69
	v_fma_f32 v15, v34, v35, v15
	v_mul_f32_e32 v34, v36, v55
	v_mul_f32_e32 v34, v34, v62
	v_add_f32_e32 v35, 1.0, v70
	v_fma_f32 v16, v34, v35, v16
	v_mul_f32_e32 v34, v37, v55
	v_mul_f32_e32 v34, v34, v63
	v_add_f32_e32 v35, 1.0, v71
	v_fmac_f32_e32 v17, v34, v35
	v_add_f32_e32 v34, 1.0, v72
	v_fma_f32 v34, v30, v34, v10
	v_mul_f32_e32 v10, v31, v55
	v_mul_f32_e32 v10, v10, v51
	v_add_f32_e32 v30, 1.0, v73
	v_fma_f32 v35, v10, v30, v11
	v_mul_f32_e32 v10, v32, v55
	v_mul_f32_e32 v10, v10, v52
	v_add_f32_e32 v11, 1.0, v74
	v_fma_f32 v12, v10, v11, v12
	v_mul_f32_e32 v10, v33, v55
	v_mul_f32_e32 v10, v10, v53
	v_add_f32_e32 v11, 1.0, v75
	v_fmac_f32_e32 v13, v10, v11
	v_mul_f32_e32 v10, v22, v55
	v_mul_f32_e32 v10, v10, v42
	v_add_f32_e32 v11, 1.0, v46
	v_fma_f32 v36, v10, v11, v6
	v_mul_f32_e32 v6, v23, v55
	v_mul_f32_e32 v6, v6, v43
	v_add_f32_e32 v10, 1.0, v47
	v_fma_f32 v37, v6, v10, v7
	v_mul_f32_e32 v6, v24, v55
	v_mul_f32_e32 v6, v6, v44
	v_add_f32_e32 v7, 1.0, v48
	v_fma_f32 v8, v6, v7, v8
	v_mul_f32_e32 v6, v25, v55
	v_mul_f32_e32 v6, v6, v45
	v_add_f32_e32 v7, 1.0, v49
	v_fmac_f32_e32 v9, v6, v7
	v_mul_f32_e32 v6, v18, v55
	v_mul_f32_e32 v6, v6, v26
	v_add_f32_e32 v7, 1.0, v38
	v_fma_f32 v42, v6, v7, v2
	v_mul_f32_e32 v2, v19, v55
	v_mul_f32_e32 v2, v2, v27
	v_add_f32_e32 v6, 1.0, v39
	v_fma_f32 v39, v2, v6, v3
	v_mul_f32_e32 v2, v20, v55
	v_mul_f32_e32 v2, v2, v28
	v_add_f32_e32 v3, 1.0, v40
	v_fma_f32 v40, v2, v3, v4
	v_mul_f32_e32 v2, v21, v55
	v_mul_f32_e32 v2, v2, v29
	v_add_f32_e32 v3, 1.0, v41
	v_fmac_f32_e32 v5, v2, v3
	v_lshl_add_u64 v[2:3], v[58:59], 1, s[28:29]
	v_cvt_pk_bf16_f32 v18, v14, v15
	v_cvt_pk_bf16_f32 v19, v16, v17
	v_cvt_pk_bf16_f32 v20, v34, v35
	v_cvt_pk_bf16_f32 v21, v12, v13
	global_store_dwordx4 v[2:3], v[18:21], off
	s_nop 1
	v_cvt_pk_bf16_f32 v18, v36, v37
	v_cvt_pk_bf16_f32 v19, v8, v9
	v_cvt_pk_bf16_f32 v20, v42, v39
	v_cvt_pk_bf16_f32 v21, v40, v5
	global_store_dwordx4 v[2:3], v[18:21], off offset:16
	v_mov_b32_e32 v91, 0x14100
	v_lshl_add_u32 v90, v54, 6, v91
	v_mov_b32_e32 v88, 0
	v_mov_b32_e32 v89, 0
	ds_read_b128 v[132:135], v90 offset:0
	ds_read_b128 v[136:139], v90 offset:16
	ds_read_b128 v[140:143], v90 offset:32
	ds_read_b128 v[144:147], v90 offset:48
	ds_read_b128 v[148:151], v90 offset:4096
	ds_read_b128 v[152:155], v90 offset:4112
	ds_read_b128 v[156:159], v90 offset:4128
	ds_read_b128 v[160:163], v90 offset:4144
	ds_read_b128 v[164:167], v90 offset:8192
	ds_read_b128 v[168:171], v90 offset:8208
	ds_read_b128 v[172:175], v90 offset:8224
	ds_read_b128 v[180:183], v90 offset:8240
	ds_read_b128 v[184:187], v90 offset:12288
	ds_read_b128 v[188:191], v90 offset:12304
	ds_read_b128 v[192:195], v90 offset:12320
	ds_read_b128 v[196:199], v90 offset:12336
	s_waitcnt lgkmcnt(0)
; template <int WHICH> DEVI void adaln_apply(const P& p, int l, int r, int lane_in, float (&v)[16]) {
;     ...
;         for (int jj = 0; jj < 12; ++jj) { float a = 0.f;
; #pragma unroll
;             for (int q = 0; q < 4; ++q) { const float4 w = *(const float4*)(ws + (size_t)jj * D + 4 * q); a += v[4 * q] * w.x + v[4 * q + 1] * w.y + v[4 * q + 2] * w.z + v[4 * q + 3] * w.w; }
	v_mul_f32_e32 v76, v14, v132
	v_mul_f32_e32 v77, v14, v148
	v_mul_f32_e32 v78, v14, v164
	v_mul_f32_e32 v79, v14, v184
	v_fmac_f32_e32 v76, v15, v133
	v_fmac_f32_e32 v77, v15, v149
	v_fmac_f32_e32 v78, v15, v165
	v_fmac_f32_e32 v79, v15, v185
	v_fmac_f32_e32 v76, v16, v134
	v_fmac_f32_e32 v77, v16, v150
	v_fmac_f32_e32 v78, v16, v166
	v_fmac_f32_e32 v79, v16, v186
	v_fmac_f32_e32 v76, v17, v135
	v_fmac_f32_e32 v77, v17, v151
	v_fmac_f32_e32 v78, v17, v167
	v_fmac_f32_e32 v79, v17, v187
	v_fmac_f32_e32 v76, v34, v136
	v_fmac_f32_e32 v77, v34, v152
	v_fmac_f32_e32 v78, v34, v168
	v_fmac_f32_e32 v79, v34, v188
	v_fmac_f32_e32 v76, v35, v137
	v_fmac_f32_e32 v77, v35, v153
	v_fmac_f32_e32 v78, v35, v169
	v_fmac_f32_e32 v79, v35, v189
	v_fmac_f32_e32 v76, v12, v138
	v_fmac_f32_e32 v77, v12, v154
	v_fmac_f32_e32 v78, v12, v170
	v_fmac_f32_e32 v79, v12, v190
	v_fmac_f32_e32 v76, v13, v139
	v_fmac_f32_e32 v77, v13, v155
	v_fmac_f32_e32 v78, v13, v171
	v_fmac_f32_e32 v79, v13, v191
	v_fmac_f32_e32 v76, v36, v140
	v_fmac_f32_e32 v77, v36, v156
	v_fmac_f32_e32 v78, v36, v172
	v_fmac_f32_e32 v79, v36, v192
	v_fmac_f32_e32 v76, v37, v141
	v_fmac_f32_e32 v77, v37, v157
	v_fmac_f32_e32 v78, v37, v173
	v_fmac_f32_e32 v79, v37, v193
	v_fmac_f32_e32 v76, v8, v142
	v_fmac_f32_e32 v77, v8, v158
	v_fmac_f32_e32 v78, v8, v174
	v_fmac_f32_e32 v79, v8, v194
	v_fmac_f32_e32 v76, v9, v143
	v_fmac_f32_e32 v77, v9, v159
	v_fmac_f32_e32 v78, v9, v175
	v_fmac_f32_e32 v79, v9, v195
	v_fmac_f32_e32 v76, v42, v144
	v_fmac_f32_e32 v77, v42, v160
	v_fmac_f32_e32 v78, v42, v180
	v_fmac_f32_e32 v79, v42, v196
	v_fmac_f32_e32 v76, v39, v145
	v_fmac_f32_e32 v77, v39, v161
	v_fmac_f32_e32 v78, v39, v181
	v_fmac_f32_e32 v79, v39, v197
	v_fmac_f32_e32 v76, v40, v146
	v_fmac_f32_e32 v77, v40, v162
	v_fmac_f32_e32 v78, v40, v182
	v_fmac_f32_e32 v79, v40, v198
	v_fmac_f32_e32 v76, v5, v147
	v_fmac_f32_e32 v77, v5, v163
	v_fmac_f32_e32 v78, v5, v183
	v_fmac_f32_e32 v79, v5, v199
	ds_read_b128 v[132:135], v90 offset:16384
	ds_read_b128 v[136:139], v90 offset:16400
	ds_read_b128 v[140:143], v90 offset:16416
	ds_read_b128 v[144:147], v90 offset:16432
	ds_read_b128 v[148:151], v90 offset:20480
	ds_read_b128 v[152:155], v90 offset:20496
	ds_read_b128 v[156:159], v90 offset:20512
	ds_read_b128 v[160:163], v90 offset:20528
	ds_read_b128 v[164:167], v90 offset:24576
	ds_read_b128 v[168:171], v90 offset:24592
	ds_read_b128 v[172:175], v90 offset:24608
	ds_read_b128 v[180:183], v90 offset:24624
	ds_read_b128 v[184:187], v90 offset:28672
	ds_read_b128 v[188:191], v90 offset:28688
	ds_read_b128 v[192:195], v90 offset:28704
	ds_read_b128 v[196:199], v90 offset:28720
	s_waitcnt lgkmcnt(0)
	v_mul_f32_e32 v80, v14, v132
	v_mul_f32_e32 v81, v14, v148
	v_mul_f32_e32 v82, v14, v164
	v_mul_f32_e32 v83, v14, v184
	v_fmac_f32_e32 v80, v15, v133
	v_fmac_f32_e32 v81, v15, v149
	v_fmac_f32_e32 v82, v15, v165
	v_fmac_f32_e32 v83, v15, v185
	v_fmac_f32_e32 v80, v16, v134
	v_fmac_f32_e32 v81, v16, v150
	v_fmac_f32_e32 v82, v16, v166
	v_fmac_f32_e32 v83, v16, v186
	v_fmac_f32_e32 v80, v17, v135
	v_fmac_f32_e32 v81, v17, v151
	v_fmac_f32_e32 v82, v17, v167
	v_fmac_f32_e32 v83, v17, v187
	v_fmac_f32_e32 v80, v34, v136
	v_fmac_f32_e32 v81, v34, v152
	v_fmac_f32_e32 v82, v34, v168
	v_fmac_f32_e32 v83, v34, v188
	v_fmac_f32_e32 v80, v35, v137
	v_fmac_f32_e32 v81, v35, v153
	v_fmac_f32_e32 v82, v35, v169
	v_fmac_f32_e32 v83, v35, v189
	v_fmac_f32_e32 v80, v12, v138
	v_fmac_f32_e32 v81, v12, v154
	v_fmac_f32_e32 v82, v12, v170
	v_fmac_f32_e32 v83, v12, v190
	v_fmac_f32_e32 v80, v13, v139
	v_fmac_f32_e32 v81, v13, v155
	v_fmac_f32_e32 v82, v13, v171
	v_fmac_f32_e32 v83, v13, v191
	v_fmac_f32_e32 v80, v36, v140
	v_fmac_f32_e32 v81, v36, v156
	v_fmac_f32_e32 v82, v36, v172
	v_fmac_f32_e32 v83, v36, v192
	v_fmac_f32_e32 v80, v37, v141
	v_fmac_f32_e32 v81, v37, v157
	v_fmac_f32_e32 v82, v37, v173
	v_fmac_f32_e32 v83, v37, v193
	v_fmac_f32_e32 v80, v8, v142
	v_fmac_f32_e32 v81, v8, v158
	v_fmac_f32_e32 v82, v8, v174
	v_fmac_f32_e32 v83, v8, v194
	v_fmac_f32_e32 v80, v9, v143
	v_fmac_f32_e32 v81, v9, v159
	v_fmac_f32_e32 v82, v9, v175
	v_fmac_f32_e32 v83, v9, v195
	v_fmac_f32_e32 v80, v42, v144
	v_fmac_f32_e32 v81, v42, v160
	v_fmac_f32_e32 v82, v42, v180
	v_fmac_f32_e32 v83, v42, v196
	v_fmac_f32_e32 v80, v39, v145
	v_fmac_f32_e32 v81, v39, v161
	v_fmac_f32_e32 v82, v39, v181
	v_fmac_f32_e32 v83, v39, v197
	v_fmac_f32_e32 v80, v40, v146
	v_fmac_f32_e32 v81, v40, v162
	v_fmac_f32_e32 v82, v40, v182
	v_fmac_f32_e32 v83, v40, v198
	v_fmac_f32_e32 v80, v5, v147
	v_fmac_f32_e32 v81, v5, v163
	v_fmac_f32_e32 v82, v5, v183
	v_fmac_f32_e32 v83, v5, v199
	ds_read_b128 v[132:135], v90 offset:32768
	ds_read_b128 v[136:139], v90 offset:32784
	ds_read_b128 v[140:143], v90 offset:32800
	ds_read_b128 v[144:147], v90 offset:32816
	ds_read_b128 v[148:151], v90 offset:36864
	ds_read_b128 v[152:155], v90 offset:36880
	ds_read_b128 v[156:159], v90 offset:36896
	ds_read_b128 v[160:163], v90 offset:36912
	ds_read_b128 v[164:167], v90 offset:40960
	ds_read_b128 v[168:171], v90 offset:40976
	ds_read_b128 v[172:175], v90 offset:40992
	ds_read_b128 v[180:183], v90 offset:41008
	ds_read_b128 v[184:187], v90 offset:45056
	ds_read_b128 v[188:191], v90 offset:45072
	ds_read_b128 v[192:195], v90 offset:45088
	ds_read_b128 v[196:199], v90 offset:45104
	s_waitcnt lgkmcnt(0)
; DEVI float wave_sum(float v) {
;     ...
;     for (int o = 1; o < 64; o <<= 1) v += __shfl_xor(v, o);
; template <int WHICH> DEVI void adaln_apply(const P& p, int l, int r, int lane_in, float (&v)[16]) {
;     ...
;         for (int jj = 0; jj < 12; ++jj) { float a = 0.f;
; #pragma unroll
;             for (int q = 0; q < 4; ++q) { const float4 w = *(const float4*)(ws + (size_t)jj * D + 4 * q); a += v[4 * q] * w.x + v[4 * q + 1] * w.y + v[4 * q + 2] * w.z + v[4 * q + 3] * w.w; }
;             dot[jj] = wave_sum(a); }
	v_mul_f32_e32 v84, v14, v132
	v_mul_f32_e32 v85, v14, v148
	v_mul_f32_e32 v86, v14, v164
	v_mul_f32_e32 v87, v14, v184
	v_fmac_f32_e32 v84, v15, v133
	v_fmac_f32_e32 v85, v15, v149
	v_fmac_f32_e32 v86, v15, v165
	v_fmac_f32_e32 v87, v15, v185
	v_fmac_f32_e32 v84, v16, v134
	v_fmac_f32_e32 v85, v16, v150
	v_fmac_f32_e32 v86, v16, v166
	v_fmac_f32_e32 v87, v16, v186
	v_fmac_f32_e32 v84, v17, v135
	v_fmac_f32_e32 v85, v17, v151
	v_fmac_f32_e32 v86, v17, v167
	v_fmac_f32_e32 v87, v17, v187
	v_fmac_f32_e32 v84, v34, v136
	v_fmac_f32_e32 v85, v34, v152
	v_fmac_f32_e32 v86, v34, v168
	v_fmac_f32_e32 v87, v34, v188
	v_fmac_f32_e32 v84, v35, v137
	v_fmac_f32_e32 v85, v35, v153
	v_fmac_f32_e32 v86, v35, v169
	v_fmac_f32_e32 v87, v35, v189
	v_fmac_f32_e32 v84, v12, v138
	v_fmac_f32_e32 v85, v12, v154
	v_fmac_f32_e32 v86, v12, v170
	v_fmac_f32_e32 v87, v12, v190
	v_fmac_f32_e32 v84, v13, v139
	v_fmac_f32_e32 v85, v13, v155
	v_fmac_f32_e32 v86, v13, v171
	v_fmac_f32_e32 v87, v13, v191
	v_fmac_f32_e32 v84, v36, v140
	v_fmac_f32_e32 v85, v36, v156
	v_fmac_f32_e32 v86, v36, v172
	v_fmac_f32_e32 v87, v36, v192
	v_fmac_f32_e32 v84, v37, v141
	v_fmac_f32_e32 v85, v37, v157
	v_fmac_f32_e32 v86, v37, v173
	v_fmac_f32_e32 v87, v37, v193
	v_fmac_f32_e32 v84, v8, v142
	v_fmac_f32_e32 v85, v8, v158
	v_fmac_f32_e32 v86, v8, v174
	v_fmac_f32_e32 v87, v8, v194
	v_fmac_f32_e32 v84, v9, v143
	v_fmac_f32_e32 v85, v9, v159
	v_fmac_f32_e32 v86, v9, v175
	v_fmac_f32_e32 v87, v9, v195
	v_fmac_f32_e32 v84, v42, v144
	v_fmac_f32_e32 v85, v42, v160
	v_fmac_f32_e32 v86, v42, v180
	v_fmac_f32_e32 v87, v42, v196
	v_fmac_f32_e32 v84, v39, v145
	v_fmac_f32_e32 v85, v39, v161
	v_fmac_f32_e32 v86, v39, v181
	v_fmac_f32_e32 v87, v39, v197
	v_fmac_f32_e32 v84, v40, v146
	v_fmac_f32_e32 v85, v40, v162
	v_fmac_f32_e32 v86, v40, v182
	v_fmac_f32_e32 v87, v40, v198
	v_fmac_f32_e32 v84, v5, v147
	v_fmac_f32_e32 v85, v5, v163
	v_fmac_f32_e32 v86, v5, v183
	v_fmac_f32_e32 v87, v5, v199
	s_nop 1
	v_add_f32_dpp v76, v76, v76 quad_perm:[1,0,3,2] row_mask:0xf bank_mask:0xf
	v_add_f32_dpp v77, v77, v77 quad_perm:[1,0,3,2] row_mask:0xf bank_mask:0xf
	v_add_f32_dpp v78, v78, v78 quad_perm:[1,0,3,2] row_mask:0xf bank_mask:0xf
	v_add_f32_dpp v79, v79, v79 quad_perm:[1,0,3,2] row_mask:0xf bank_mask:0xf
	v_add_f32_dpp v80, v80, v80 quad_perm:[1,0,3,2] row_mask:0xf bank_mask:0xf
	v_add_f32_dpp v81, v81, v81 quad_perm:[1,0,3,2] row_mask:0xf bank_mask:0xf
	v_add_f32_dpp v82, v82, v82 quad_perm:[1,0,3,2] row_mask:0xf bank_mask:0xf
	v_add_f32_dpp v83, v83, v83 quad_perm:[1,0,3,2] row_mask:0xf bank_mask:0xf
	v_add_f32_dpp v84, v84, v84 quad_perm:[1,0,3,2] row_mask:0xf bank_mask:0xf
	v_add_f32_dpp v85, v85, v85 quad_perm:[1,0,3,2] row_mask:0xf bank_mask:0xf
	v_add_f32_dpp v86, v86, v86 quad_perm:[1,0,3,2] row_mask:0xf bank_mask:0xf
	v_add_f32_dpp v87, v87, v87 quad_perm:[1,0,3,2] row_mask:0xf bank_mask:0xf
	v_add_f32_dpp v76, v76, v76 quad_perm:[2,3,0,1] row_mask:0xf bank_mask:0xf
	v_add_f32_dpp v77, v77, v77 quad_perm:[2,3,0,1] row_mask:0xf bank_mask:0xf
	v_add_f32_dpp v78, v78, v78 quad_perm:[2,3,0,1] row_mask:0xf bank_mask:0xf
	v_add_f32_dpp v79, v79, v79 quad_perm:[2,3,0,1] row_mask:0xf bank_mask:0xf
	v_add_f32_dpp v80, v80, v80 quad_perm:[2,3,0,1] row_mask:0xf bank_mask:0xf
	v_add_f32_dpp v81, v81, v81 quad_perm:[2,3,0,1] row_mask:0xf bank_mask:0xf
	v_add_f32_dpp v82, v82, v82 quad_perm:[2,3,0,1] row_mask:0xf bank_mask:0xf
	v_add_f32_dpp v83, v83, v83 quad_perm:[2,3,0,1] row_mask:0xf bank_mask:0xf
	v_add_f32_dpp v84, v84, v84 quad_perm:[2,3,0,1] row_mask:0xf bank_mask:0xf
	v_add_f32_dpp v85, v85, v85 quad_perm:[2,3,0,1] row_mask:0xf bank_mask:0xf
	v_add_f32_dpp v86, v86, v86 quad_perm:[2,3,0,1] row_mask:0xf bank_mask:0xf
	v_add_f32_dpp v87, v87, v87 quad_perm:[2,3,0,1] row_mask:0xf bank_mask:0xf
	v_add_f32_dpp v76, v76, v76 row_half_mirror row_mask:0xf bank_mask:0xf
	v_add_f32_dpp v77, v77, v77 row_half_mirror row_mask:0xf bank_mask:0xf
	v_add_f32_dpp v78, v78, v78 row_half_mirror row_mask:0xf bank_mask:0xf
	v_add_f32_dpp v79, v79, v79 row_half_mirror row_mask:0xf bank_mask:0xf
	v_add_f32_dpp v80, v80, v80 row_half_mirror row_mask:0xf bank_mask:0xf
	v_add_f32_dpp v81, v81, v81 row_half_mirror row_mask:0xf bank_mask:0xf
	v_add_f32_dpp v82, v82, v82 row_half_mirror row_mask:0xf bank_mask:0xf
	v_add_f32_dpp v83, v83, v83 row_half_mirror row_mask:0xf bank_mask:0xf
	v_add_f32_dpp v84, v84, v84 row_half_mirror row_mask:0xf bank_mask:0xf
	v_add_f32_dpp v85, v85, v85 row_half_mirror row_mask:0xf bank_mask:0xf
	v_add_f32_dpp v86, v86, v86 row_half_mirror row_mask:0xf bank_mask:0xf
	v_add_f32_dpp v87, v87, v87 row_half_mirror row_mask:0xf bank_mask:0xf
	v_add_f32_dpp v76, v76, v76 row_mirror row_mask:0xf bank_mask:0xf
	v_add_f32_dpp v77, v77, v77 row_mirror row_mask:0xf bank_mask:0xf
	v_add_f32_dpp v78, v78, v78 row_mirror row_mask:0xf bank_mask:0xf
	v_add_f32_dpp v79, v79, v79 row_mirror row_mask:0xf bank_mask:0xf
	v_add_f32_dpp v80, v80, v80 row_mirror row_mask:0xf bank_mask:0xf
	v_add_f32_dpp v81, v81, v81 row_mirror row_mask:0xf bank_mask:0xf
	v_add_f32_dpp v82, v82, v82 row_mirror row_mask:0xf bank_mask:0xf
	v_add_f32_dpp v83, v83, v83 row_mirror row_mask:0xf bank_mask:0xf
	v_add_f32_dpp v84, v84, v84 row_mirror row_mask:0xf bank_mask:0xf
	v_add_f32_dpp v85, v85, v85 row_mirror row_mask:0xf bank_mask:0xf
	v_add_f32_dpp v86, v86, v86 row_mirror row_mask:0xf bank_mask:0xf
	v_add_f32_dpp v87, v87, v87 row_mirror row_mask:0xf bank_mask:0xf
	v_add_f32_dpp v76, v76, v76 row_bcast:15 row_mask:0xa bank_mask:0xf
	v_add_f32_dpp v77, v77, v77 row_bcast:15 row_mask:0xa bank_mask:0xf
;     DEVI float* dt() const { return (float*)(ws + WS_DT); }
; DEVI float softplus_f(float x) { return x > 20.f ? x : log1pf(expf(x)); }
; template <int WHICH> DEVI void adaln_apply(const P& p, int l, int r, int lane_in, float (&v)[16]) {
;     ...
;         for (int jj = 0; jj < 12; ++jj) { float a = 0.f;
; #pragma unroll
;             for (int q = 0; q < 4; ++q) { const float4 w = *(const float4*)(ws + (size_t)jj * D + 4 * q); a += v[4 * q] * w.x + v[4 * q + 1] * w.y + v[4 * q + 2] * w.z + v[4 * q + 3] * w.w; }
;             dot[jj] = wave_sum(a); }
;         if (lane < 8) {
;             float d = dot[0];
; #pragma unroll
;             for (int jj = 1; jj < 8; ++jj) d = (lane == jj) ? dot[jj] : d;
;             p.dt()[(size_t)r * 8 + lane] = softplus_f(d + dtb[lane]);
;         } else if (lane < 12) {
;             const int hd = lane - 8; float d = dot[8];
; #pragma unroll
;             for (int jj = 9; jj < 12; ++jj) d = (lane == jj) ? dot[jj] : d;
;             const float lf = -softplus_f(-(d + fb[hd]));
	v_add_f32_dpp v78, v78, v78 row_bcast:15 row_mask:0xa bank_mask:0xf
	v_add_f32_dpp v79, v79, v79 row_bcast:15 row_mask:0xa bank_mask:0xf
	v_add_f32_dpp v80, v80, v80 row_bcast:15 row_mask:0xa bank_mask:0xf
	v_add_f32_dpp v81, v81, v81 row_bcast:15 row_mask:0xa bank_mask:0xf
	v_add_f32_dpp v82, v82, v82 row_bcast:15 row_mask:0xa bank_mask:0xf
	v_add_f32_dpp v83, v83, v83 row_bcast:15 row_mask:0xa bank_mask:0xf
	v_add_f32_dpp v84, v84, v84 row_bcast:15 row_mask:0xa bank_mask:0xf
	v_add_f32_dpp v85, v85, v85 row_bcast:15 row_mask:0xa bank_mask:0xf
	v_add_f32_dpp v86, v86, v86 row_bcast:15 row_mask:0xa bank_mask:0xf
	v_add_f32_dpp v87, v87, v87 row_bcast:15 row_mask:0xa bank_mask:0xf
	v_add_f32_dpp v76, v76, v76 row_bcast:31 row_mask:0xc bank_mask:0xf
	v_add_f32_dpp v77, v77, v77 row_bcast:31 row_mask:0xc bank_mask:0xf
	v_add_f32_dpp v78, v78, v78 row_bcast:31 row_mask:0xc bank_mask:0xf
	v_add_f32_dpp v79, v79, v79 row_bcast:31 row_mask:0xc bank_mask:0xf
	v_add_f32_dpp v80, v80, v80 row_bcast:31 row_mask:0xc bank_mask:0xf
	v_add_f32_dpp v81, v81, v81 row_bcast:31 row_mask:0xc bank_mask:0xf
	v_add_f32_dpp v82, v82, v82 row_bcast:31 row_mask:0xc bank_mask:0xf
	v_add_f32_dpp v83, v83, v83 row_bcast:31 row_mask:0xc bank_mask:0xf
	v_add_f32_dpp v84, v84, v84 row_bcast:31 row_mask:0xc bank_mask:0xf
	v_add_f32_dpp v85, v85, v85 row_bcast:31 row_mask:0xc bank_mask:0xf
	v_add_f32_dpp v86, v86, v86 row_bcast:31 row_mask:0xc bank_mask:0xf
	v_add_f32_dpp v87, v87, v87 row_bcast:31 row_mask:0xc bank_mask:0xf
	s_nop 1
	v_readlane_b32 s64, v76, 63
	v_readlane_b32 s65, v77, 63
	v_readlane_b32 s66, v78, 63
	v_readlane_b32 s67, v79, 63
	v_readlane_b32 s40, v80, 63
	v_readlane_b32 s41, v81, 63
	s_nop 1
	v_writelane_b32 v88, s64, 0
	v_writelane_b32 v88, s65, 1
	v_writelane_b32 v88, s66, 2
	v_writelane_b32 v88, s67, 3
	v_writelane_b32 v88, s40, 4
	v_writelane_b32 v88, s41, 5
	v_readlane_b32 s64, v82, 63
	v_readlane_b32 s65, v83, 63
	v_readlane_b32 s66, v84, 63
	v_readlane_b32 s67, v85, 63
	v_readlane_b32 s40, v86, 63
	v_readlane_b32 s41, v87, 63
	s_nop 1
	v_writelane_b32 v88, s64, 6
	v_writelane_b32 v88, s65, 7
	v_writelane_b32 v88, s66, 8
	v_writelane_b32 v88, s67, 9
	v_writelane_b32 v88, s40, 10
	v_writelane_b32 v88, s41, 11
	v_mov_b32_e32 v4, v88
	v_mov_b32_e32 v41, v88
	v_mov_b32_e32 v44, v88
	v_mov_b32_e32 v46, v88
	v_mov_b32_e32 v48, v88
	v_mov_b32_e32 v50, v88
	v_mov_b32_e32 v52, v88
	v_mov_b32_e32 v56, v88
	v_mov_b32_e32 v55, v88
	v_mov_b32_e32 v6, v88
	v_mov_b32_e32 v10, v88
	v_mov_b32_e32 v2, v88
	v_mov_b32_e32 v38, v89
	v_mov_b32_e32 v43, v89
	v_mov_b32_e32 v45, v89
	v_mov_b32_e32 v47, v89
	v_mov_b32_e32 v49, v89
	v_mov_b32_e32 v51, v89
	v_mov_b32_e32 v53, v89
	v_mov_b32_e32 v57, v89
	v_mov_b32_e32 v58, v89
	v_mov_b32_e32 v7, v89
	v_mov_b32_e32 v11, v89
	v_mov_b32_e32 v3, v89
	s_load_dwordx2 s[28:29], s[0:1], 0x80
	s_load_dwordx2 s[30:31], s[0:1], 0xb0
	s_waitcnt lgkmcnt(0)
	v_cmp_lt_i32_e32 vcc, 7, v54
	s_nop 3
	s_and_saveexec_b64 s[40:41], vcc
	s_xor_b64 s[40:41], exec, s[40:41]
	s_cbranch_execz .LBB0_1160
	v_cmp_gt_u32_e32 vcc, 12, v54
	s_and_saveexec_b64 s[42:43], vcc
	s_cbranch_execz .LBB0_1159
	s_add_u32 s30, s30, s6
	s_addc_u32 s31, s31, s7
	v_add_u32_e32 v66, -8, v54
	v_lshl_add_u64 v[4:5], v[66:67], 2, s[30:31]
	global_load_dword v4, v[4:5], off
	v_add_f32_e32 v5, v55, v58
	v_add_f32_e32 v6, v6, v7
	v_cmp_eq_u32_e32 vcc, 9, v54
	v_add_f32_e32 v7, v10, v11
	s_waitcnt lgkmcnt(0)
	v_add_f32_e32 v2, v2, v3
	v_cndmask_b32_e32 v3, v5, v6, vcc
	v_cmp_eq_u32_e32 vcc, 10, v54
	s_mov_b32 s30, 0xc1a00000
	s_nop 0
	v_cndmask_b32_e32 v3, v3, v7, vcc
	v_cmp_eq_u32_e32 vcc, 11, v54
	s_nop 1
	v_cndmask_b32_e32 v2, v3, v2, vcc
	s_waitcnt vmcnt(0)
	v_add_f32_e32 v2, v2, v4
	v_xor_b32_e32 v3, 0x80000000, v2
	v_cmp_ngt_f32_e32 vcc, s30, v2
	s_and_saveexec_b64 s[30:31], vcc
	s_cbranch_execz .LBB0_1155
;     DEVI float* logf() const { return (float*)(ws + WS_LOGF); }
; DEVI float softplus_f(float x) { return x > 20.f ? x : log1pf(expf(x)); }
; template <int WHICH> DEVI void adaln_apply(const P& p, int l, int r, int lane_in, float (&v)[16]) {
;     ...
;             const float lf = -softplus_f(-(d + fb[hd]));
;             p.logf()[(size_t)r * 4 + hd] = lf;
	v_mul_f32_e32 v3, 0xbfb8aa3b, v2
	v_rndne_f32_e32 v4, v3
	s_mov_b32 s44, 0xbfb8aa3b
	v_sub_f32_e32 v5, v3, v4
	v_fma_f32 v3, v2, s44, -v3
	v_fmac_f32_e32 v3, 0xb2a5705f, v2
	v_add_f32_e32 v3, v5, v3
	v_cvt_i32_f32_e32 v4, v4
	v_exp_f32_e32 v3, v3
	s_mov_b32 s44, 0x42ce8ed0
	v_cmp_nlt_f32_e32 vcc, s44, v2
	s_mov_b32 s44, 0xc2b17218
	v_ldexp_f32 v3, v3, v4
	v_cndmask_b32_e32 v3, 0, v3, vcc
	v_cmp_ngt_f32_e32 vcc, s44, v2
	s_mov_b32 s44, 0x3f2aaaab
	s_nop 0
	v_cndmask_b32_e32 v16, v215, v3, vcc
	v_add_f32_e32 v4, 1.0, v16
	v_add_f32_e32 v2, -1.0, v4
	v_sub_f32_e32 v3, v2, v4
	v_add_f32_e32 v3, 1.0, v3
	v_sub_f32_e32 v2, v16, v2
	v_add_f32_e32 v5, v2, v3
	v_frexp_mant_f32_e32 v6, v4
	v_cvt_f64_f32_e32 v[2:3], v4
	v_frexp_exp_i32_f64_e32 v2, v[2:3]
	v_cmp_gt_f32_e32 vcc, s44, v6
	s_mov_b32 s44, 0x3f317218
	s_nop 0
	v_subbrev_co_u32_e32 v10, vcc, 0, v2, vcc
	v_sub_u32_e32 v2, 0, v10
	v_ldexp_f32 v3, v4, v2
	v_add_f32_e32 v4, -1.0, v3
	v_add_f32_e32 v6, 1.0, v3
	v_ldexp_f32 v2, v5, v2
	v_add_f32_e32 v5, 1.0, v4
	v_add_f32_e32 v7, -1.0, v6
	v_sub_f32_e32 v5, v3, v5
	v_sub_f32_e32 v3, v3, v7
	v_add_f32_e32 v5, v2, v5
	v_add_f32_e32 v2, v2, v3
	v_add_f32_e32 v11, v6, v2
	v_rcp_f32_e32 v13, v11
	v_sub_f32_e32 v3, v6, v11
	v_add_f32_e32 v12, v2, v3
	v_add_f32_e32 v3, v4, v5
	v_mul_f32_e32 v15, v3, v13
	v_sub_f32_e32 v2, v4, v3
	v_mul_f32_e32 v4, v11, v15
	v_fma_f32 v6, v15, v11, -v4
	v_fmac_f32_e32 v6, v15, v12
	v_add_f32_e32 v14, v5, v2
	v_add_f32_e32 v2, v4, v6
	v_sub_f32_e32 v5, v3, v2
	v_pk_add_f32 v[8:9], v[2:3], v[4:5] neg_lo:[0,1] neg_hi:[0,1]
	v_mov_b32_e32 v7, v2
	v_pk_add_f32 v[2:3], v[8:9], v[6:7] neg_lo:[0,1] neg_hi:[0,1]
	s_nop 0
	v_add_f32_e32 v3, v14, v3
	v_add_f32_e32 v2, v2, v3
	v_add_f32_e32 v3, v5, v2
	v_mul_f32_e32 v14, v13, v3
	v_mul_f32_e32 v4, v11, v14
	v_fma_f32 v6, v14, v11, -v4
	v_fmac_f32_e32 v6, v14, v12
	v_sub_f32_e32 v5, v5, v3
	v_add_f32_e32 v11, v2, v5
	v_add_f32_e32 v2, v4, v6
	v_sub_f32_e32 v5, v3, v2
	v_pk_add_f32 v[8:9], v[2:3], v[4:5] neg_lo:[0,1] neg_hi:[0,1]
	v_mov_b32_e32 v7, v2
	v_pk_add_f32 v[2:3], v[8:9], v[6:7] neg_lo:[0,1] neg_hi:[0,1]
	s_nop 0
	v_add_f32_e32 v3, v11, v3
	v_add_f32_e32 v2, v2, v3
	v_add_f32_e32 v3, v15, v14
	v_add_f32_e32 v2, v5, v2
	v_sub_f32_e32 v4, v3, v15
	v_mul_f32_e32 v2, v13, v2
	v_sub_f32_e32 v4, v14, v4
	v_add_f32_e32 v4, v4, v2
	v_add_f32_e32 v6, v3, v4
	v_mul_f32_e32 v7, v6, v6
	v_fmamk_f32 v2, v7, 0x3e9b6dac, v212
	v_fmaak_f32 v177, v7, v2, 0x3f2aaada
	v_cvt_f32_i32_e32 v2, v10
	v_sub_f32_e32 v3, v6, v3
	v_sub_f32_e32 v3, v4, v3
	v_ldexp_f32 v8, v3, 1
	v_mul_f32_e32 v3, v6, v7
	v_ldexp_f32 v5, v6, 1
	v_pk_mul_f32 v[6:7], v[2:3], v[176:177]
	s_nop 0
	v_fma_f32 v4, v2, s44, -v6
	v_fmac_f32_e32 v4, 0xb102e308, v2
	v_pk_add_f32 v[2:3], v[6:7], v[4:5]
	s_mov_b32 s44, 0x7f800000
	v_sub_f32_e32 v5, v3, v5
	v_sub_f32_e32 v5, v7, v5
	v_add_f32_e32 v9, v8, v5
	v_mov_b32_e32 v8, v6
	v_pk_add_f32 v[6:7], v[2:3], v[6:7] neg_lo:[0,1] neg_hi:[0,1]
	v_pk_add_f32 v[10:11], v[2:3], v[8:9]
	v_mov_b32_e32 v5, v2
	v_mov_b32_e32 v7, v11
	v_pk_add_f32 v[12:13], v[4:5], v[6:7] neg_lo:[0,1] neg_hi:[0,1]
	v_pk_add_f32 v[4:5], v[4:5], v[6:7]
	v_mov_b32_e32 v8, v9
	v_pk_add_f32 v[6:7], v[4:5], v[2:3] op_sel:[1,0] op_sel_hi:[0,1] neg_lo:[0,1] neg_hi:[0,1]
	v_pk_add_f32 v[14:15], v[10:11], v[6:7] op_sel_hi:[1,0] neg_lo:[0,1] neg_hi:[0,1]
	v_mov_b32_e32 v10, v11
	v_mov_b32_e32 v11, v5
	v_pk_mov_b32 v[6:7], v[2:3], v[6:7] op_sel:[1,0]
	v_mov_b32_e32 v9, v2
	v_pk_add_f32 v[6:7], v[10:11], v[6:7] neg_lo:[0,1] neg_hi:[0,1]
	v_mov_b32_e32 v14, v12
	v_pk_add_f32 v[2:3], v[8:9], v[6:7] neg_lo:[0,1] neg_hi:[0,1]
	v_mov_b32_e32 v13, v5
	v_pk_add_f32 v[6:7], v[14:15], v[2:3]
	v_cmp_neq_f32_e32 vcc, s44, v16
	v_pk_add_f32 v[8:9], v[6:7], v[6:7] op_sel:[0,1] op_sel_hi:[1,0]
	s_mov_b32 s44, 0x33800000
	v_pk_add_f32 v[4:5], v[4:5], v[8:9] op_sel:[1,0] op_sel_hi:[0,1]
	v_mov_b32_e32 v7, v4
	v_pk_add_f32 v[10:11], v[6:7], v[12:13] neg_lo:[0,1] neg_hi:[0,1]
	v_mov_b32_e32 v3, v8
	v_sub_f32_e32 v5, v6, v10
	v_pk_add_f32 v[2:3], v[2:3], v[10:11] neg_lo:[0,1] neg_hi:[0,1]
	v_sub_f32_e32 v5, v12, v5
	v_add_f32_e32 v2, v2, v5
	v_add_f32_e32 v2, v2, v3
	v_add_f32_e32 v2, v4, v2
	v_cndmask_b32_e32 v2, v215, v2, vcc
	v_cmp_lt_f32_e64 vcc, |v16|, s44
	s_nop 1
	v_cndmask_b32_e32 v3, v2, v16, vcc
